# phase-start stagger: odd row-tile workgroups sleep about half an epilogue burst before each GEMM phase
# baseline (speedup 1.0000x reference)
; __device__ __forceinline__ f32x2 unpk_f16(unsigned u) { const h16x2_t h = __builtin_bit_cast(h16x2_t, u); return __builtin_convertvector(h, f32x2); }
; __device__ __forceinline__ float rstd_of(u64 ssq) { return frsq((float)ssq * (1.0f / (2048.0f * 16777216.0f)) + EPS); }
; __global__ void __launch_bounds__(NTHREADS, 2) fwd_kernel(Args a) {
;     ...
;         bf16_t* HB = (bf16_t*)(ws + WS_HB); bf16_t* MB = (bf16_t*)(ws + WS_MB); bf16_t* MEMB = (bf16_t*)(ws + WS_MEMB); bf16_t* KVB = (bf16_t*)(ws + WS_KV);
;         bf16_t* ACT = (bf16_t*)(ws + WS_ACT); bf16_t* XQB = (bf16_t*)(ws + WS_XQB); bf16_t* XOB = (bf16_t*)(ws + WS_XOB);
;         float* M32 = (float*)(ws + WS_M32);
;         if (ph == 2 * NPL) {
;             const u64* ssq = ssq_all + (size_t)8 * T; const float* fg = AIN(27);
;             const int lane = tid & 63, gw = bx * 8 + (tid >> 6), nw = G * 8;
;             for (int r = gw; r < T; r += nw) {
;                 const float rs = rstd_of(ssq[r]); const bf16_t* hr = (const bf16_t*)(ws + WS_H16) + (size_t)r * D; float* orow = out + (size_t)r * D;
; #pragma unroll
;                 for (int i = 0; i < 8; ++i) { const int cidx = (i * 64 + lane) * 4; const u32x2 hw = *(const u32x2*)(hr + cidx); const f32x4 gg = *(const f32x4*)(fg + cidx);
;                     const f32x2 a2 = unpk_f16(hw.x), b2 = unpk_f16(hw.y); f32x4 v; v[0] = a2.x; v[1] = a2.y; v[2] = b2.x; v[3] = b2.y; *(f32x4*)(orow + cidx) = v * rs * gg; }
;             }
;         } else {
;             const int l = ph / NPL, k = ph - l * NPL;
;             switch (k) {
.LBB0_12:
	s_mul_hi_i32 s2, s38, 0x4ec4ec4f
	s_lshr_b32 s3, s2, 31
	s_ashr_i32 s2, s2, 2
	s_add_i32 s78, s2, s3
	s_mul_i32 s40, s78, -13
	s_add_i32 s40, s40, s38
	s_mov_b32 s2, 0
	s_cmp_eq_u32 s40, 1
	s_cselect_b32 s2, 38, s2
	s_cmp_eq_u32 s40, 2
	s_cselect_b32 s2, 300, s2
	s_cmp_eq_u32 s40, 3
	s_cselect_b32 s2, 50, s2
	s_cmp_eq_u32 s40, 6
	s_cselect_b32 s2, 150, s2
	s_cmp_eq_u32 s40, 7
	s_cselect_b32 s2, 300, s2
	s_cmp_eq_u32 s40, 10
	s_cselect_b32 s2, 300, s2
	s_cmp_eq_u32 s40, 11
	s_cselect_b32 s2, 38, s2
	s_cmp_eq_u32 s40, 12
	s_cselect_b32 s2, 300, s2
	s_bitcmp1_b32 s39, 3
	s_cselect_b32 s2, s2, 0
.Lstag_loop:
	s_cmp_eq_u32 s2, 0
	s_cbranch_scc1 .Lstag_done
	s_sleep 1
	s_sub_u32 s2, s2, 1
	s_branch .Lstag_loop
.Lstag_done:
	s_waitcnt lgkmcnt(0)
	s_add_u32 s75, s22, 0xd905000
	s_addc_u32 s2, s23, 0
	s_add_u32 s80, s22, 0xda29000
	s_addc_u32 s81, s23, 0
	s_add_u32 s8, s22, 0x11a29000
	s_addc_u32 s9, s23, 0
	v_writelane_b32 v255, s2, 10
	s_add_u32 s64, s22, 0x167a9000
	s_mov_b64 s[4:5], 0
	s_addc_u32 s65, s23, 0
	v_writelane_b32 v255, s4, 11
	s_add_u32 s88, s22, 0x327a9000
	s_addc_u32 s89, s23, 0
	v_writelane_b32 v255, s5, 12
	s_mov_b64 s[4:5], 0
	v_writelane_b32 v255, s4, 13
	s_mov_b64 s[2:3], -1
	s_mov_b64 s[12:13], 0
	s_cmp_lt_i32 s40, 6
	v_writelane_b32 v255, s5, 14
	s_cbranch_scc1 .LBB0_219
	s_add_u32 s14, s22, 0x16229000
	s_addc_u32 s15, s23, 0
	s_cmp_gt_i32 s40, 8
	s_cbranch_scc0 .LBB0_17
	s_cmp_gt_i32 s40, 10
	s_cbranch_scc0 .LBB0_18
	s_mov_b64 s[4:5], -1
	v_writelane_b32 v255, s4, 11
	s_mov_b64 s[2:3], 0
	s_cmp_gt_i32 s40, 11
	v_writelane_b32 v255, s5, 12
	s_mov_b64 s[4:5], 0
	s_cbranch_scc0 .LBB0_19
	v_writelane_b32 v255, s4, 11
	s_cmp_eq_u32 s40, 12
	s_nop 0
	v_writelane_b32 v255, s5, 12
	s_cselect_b64 s[4:5], -1, 0
	s_branch .LBB0_19
